# spatial-gating: LayerNorm gain/bias vectors (identical for the four 512-element sub-chunks of a thread) loaded once per channel group instead of four serialized reloads, on top of v44
# speedup vs baseline: 1.0030x; 1.0030x over previous
; __device__ __forceinline__ unsigned cvt_pk_bf16(float lo, float hi) { unsigned r; asm volatile("v_cvt_pk_bf16_f32 %0, %1, %2" : "=v"(r) : "v"(lo), "v"(hi)); return r; }
; #define LAS __attribute__((address_space(3)))
; #define GAS __attribute__((address_space(1)))
; DI float bf_lo(unsigned w) { return __uint_as_float(w << 16); }
; DI float bf_hi(unsigned w) { return __uint_as_float(w & 0xffff0000u); }
; DI void phase_mix(const Ctx& C, bf16_t* Z, const float* lse_, int L, bool dry) {
;     ...
;         for (int g = 0; g < 4; ++g) {
;         const int tkE = 16 * w + fr;
;         bf16_t* up = Z + (size_t)(row0 + tkE) * ZW + CU + g * 128 + 4 * fq;
;         u32x2 uq[8];
; #pragma unroll
;         for (int ct = 0; ct < 8; ++ct) uq[ct] = __builtin_nontemporal_load((const GAS u32x2*)(up + 16 * ct));
;         const float bias = sg_b[g * 128 + tkE];
; #pragma unroll
;         for (int cc = 0; cc < 4; ++cc) {
;             const int c = tid + cc * 512, tk = c >> 4, ch = c & 15, c0 = g * 128 + ch * 8;
;             const u32x4 rw = raw[cc];
;             const float mean = stat[tk * 2], rstd = stat[tk * 2 + 1];
;             const f32x4 g0 = *(const GAS f32x4*)(ln_g + c0), g1 = *(const GAS f32x4*)(ln_g + c0 + 4), b0 = *(const GAS f32x4*)(ln_b + c0), b1 = *(const GAS f32x4*)(ln_b + c0 + 4);
;             LAS bf16_t* vp = Vt2 + (ch * 8) * 136 + (tk ^ (ch << 3));
;             const unsigned p0 = cvt_pk_bf16((bf_lo(rw.x) - mean) * rstd * g0.x + b0.x, (bf_hi(rw.x) - mean) * rstd * g0.y + b0.y);
;             const unsigned p1 = cvt_pk_bf16((bf_lo(rw.y) - mean) * rstd * g0.z + b0.z, (bf_hi(rw.y) - mean) * rstd * g0.w + b0.w);
;             const unsigned p2 = cvt_pk_bf16((bf_lo(rw.z) - mean) * rstd * g1.x + b1.x, (bf_hi(rw.z) - mean) * rstd * g1.y + b1.y);
;             const unsigned p3 = cvt_pk_bf16((bf_lo(rw.w) - mean) * rstd * g1.z + b1.z, (bf_hi(rw.w) - mean) * rstd * g1.w + b1.w);
;             vp[0 * 136] = (bf16_t)(p0 & 0xffffu); vp[1 * 136] = (bf16_t)(p0 >> 16); vp[2 * 136] = (bf16_t)(p1 & 0xffffu); vp[3 * 136] = (bf16_t)(p1 >> 16);
;             vp[4 * 136] = (bf16_t)(p2 & 0xffffu); vp[5 * 136] = (bf16_t)(p2 >> 16); vp[6 * 136] = (bf16_t)(p3 & 0xffffu); vp[7 * 136] = (bf16_t)(p3 >> 16);
;         }
.LBB0_194:
	s_lshl_b32 s1, s0, 7
	v_add_u32_e32 v192, s1, v90
	v_lshl_add_u64 v[36:37], v[192:193], 2, s[10:11]
	v_or_b32_e32 v192, s1, v91
	v_lshlrev_b64 v[16:17], 2, v[192:193]
	v_lshl_add_u64 v[26:27], s[8:9], 0, v[16:17]
	v_lshl_add_u64 v[24:25], s[6:7], 0, v[16:17]
	global_load_dwordx4 v[20:23], v[26:27], off
	global_load_dwordx4 v[28:31], v[24:25], off
	global_load_dwordx4 v[32:35], v[24:25], off offset:16
	global_load_dwordx4 v[16:19], v[26:27], off offset:16
	ds_read_b64 v[38:39], v111 offset:34816
	s_lshl_b32 s34, s0, 8
	s_waitcnt vmcnt(7)
	v_lshlrev_b32_e32 v40, 16, v0
	v_and_b32_e32 v41, 0xffff0000, v0
	v_lshlrev_b32_e32 v42, 16, v1
	v_and_b32_e32 v43, 0xffff0000, v1
	v_lshlrev_b32_e32 v44, 16, v2
	v_and_b32_e32 v45, 0xffff0000, v2
	v_lshlrev_b32_e32 v46, 16, v3
	v_and_b32_e32 v47, 0xffff0000, v3
	v_lshl_add_u64 v[70:71], v[66:67], 0, s[34:35]
	global_load_dwordx2 v[86:87], v[70:71], off nt
	global_load_dwordx2 v[84:85], v[70:71], off offset:32 nt
	global_load_dwordx2 v[82:83], v[70:71], off offset:64 nt
	global_load_dwordx2 v[80:81], v[70:71], off offset:96 nt
	global_load_dwordx2 v[78:79], v[70:71], off offset:128 nt
	global_load_dwordx2 v[76:77], v[70:71], off offset:160 nt
	global_load_dwordx2 v[74:75], v[70:71], off offset:192 nt
	global_load_dwordx2 v[72:73], v[70:71], off offset:224 nt
	global_load_dword v53, v[36:37], off
	s_waitcnt lgkmcnt(0)
	v_sub_f32_e32 v36, v40, v38
	v_sub_f32_e32 v37, v41, v38
	v_sub_f32_e32 v40, v42, v38
	v_sub_f32_e32 v41, v43, v38
	v_sub_f32_e32 v42, v44, v38
	v_sub_f32_e32 v43, v45, v38
	v_sub_f32_e32 v44, v46, v38
	v_sub_f32_e32 v38, v47, v38
	v_mul_f32_e32 v36, v39, v36
	v_mul_f32_e32 v37, v39, v37
	v_mul_f32_e32 v40, v39, v40
	v_mul_f32_e32 v41, v39, v41
	v_mul_f32_e32 v42, v39, v42
	v_mul_f32_e32 v43, v39, v43
	v_mul_f32_e32 v44, v39, v44
	v_mul_f32_e32 v38, v39, v38
	s_waitcnt vmcnt(15)
	v_and_b32_e32 v45, 0xffff0000, v5
	v_lshlrev_b32_e32 v46, 16, v6
	v_and_b32_e32 v47, 0xffff0000, v6
	v_lshlrev_b32_e32 v55, 16, v7
	v_and_b32_e32 v57, 0xffff0000, v7
	s_cmp_eq_u32 s0, 3
	s_waitcnt vmcnt(9)
	v_mov_b32_e32 v156, v20
	v_mov_b32_e32 v157, v21
	v_mov_b32_e32 v158, v22
	v_mov_b32_e32 v159, v23
	v_mov_b32_e32 v160, v28
	v_mov_b32_e32 v161, v29
	v_mov_b32_e32 v162, v30
	v_mov_b32_e32 v163, v31
	v_mov_b32_e32 v164, v32
	v_mov_b32_e32 v165, v33
	v_mov_b32_e32 v166, v34
	v_mov_b32_e32 v167, v35
	v_mov_b32_e32 v168, v16
	v_mov_b32_e32 v169, v17
	v_mov_b32_e32 v170, v18
	v_mov_b32_e32 v171, v19
	s_waitcnt vmcnt(11)
	v_fma_f32 v20, v36, v28, v20
	v_fma_f32 v21, v37, v29, v21
	v_fma_f32 v22, v40, v30, v22
	v_fmac_f32_e32 v23, v41, v31
	s_waitcnt vmcnt(9)
	v_fma_f32 v16, v42, v32, v16
	v_fma_f32 v17, v43, v33, v17
	v_fma_f32 v18, v44, v34, v18
	v_fmac_f32_e32 v19, v38, v35
	v_cvt_pk_bf16_f32 v38, v20, v21
	v_cvt_pk_bf16_f32 v39, v22, v23
	v_cvt_pk_bf16_f32 v40, v16, v17
	v_cvt_pk_bf16_f32 v41, v18, v19
	v_mov_b32_e32 v16, v156
	v_mov_b32_e32 v17, v157
	v_mov_b32_e32 v18, v158
	v_mov_b32_e32 v19, v159
	v_mov_b32_e32 v20, v160
	v_mov_b32_e32 v21, v161
	v_mov_b32_e32 v22, v162
	v_mov_b32_e32 v23, v163
	v_mov_b32_e32 v28, v164
	v_mov_b32_e32 v29, v165
	v_mov_b32_e32 v30, v166
	v_mov_b32_e32 v31, v167
	v_mov_b32_e32 v32, v168
	v_mov_b32_e32 v33, v169
	v_mov_b32_e32 v34, v170
	v_mov_b32_e32 v35, v171
	ds_read_b64 v[36:37], v112 offset:34816
	v_lshlrev_b32_e32 v42, 16, v4
	v_and_b32_e32 v43, 0xffff0000, v4
	v_lshlrev_b32_e32 v44, 16, v5
	ds_write_b16 v98, v38
	ds_write_b16_d16_hi v98, v38 offset:272
	ds_write_b16 v98, v39 offset:544
	ds_write_b16_d16_hi v98, v39 offset:816
	ds_write_b16 v98, v40 offset:1088
	ds_write_b16_d16_hi v98, v40 offset:1360
	ds_write_b16 v98, v41 offset:1632
	ds_write_b16_d16_hi v98, v41 offset:1904
	s_waitcnt lgkmcnt(8)
	v_sub_f32_e32 v38, v42, v36
	v_sub_f32_e32 v39, v43, v36
	v_sub_f32_e32 v40, v44, v36
	v_sub_f32_e32 v41, v45, v36
	v_sub_f32_e32 v42, v46, v36
	v_sub_f32_e32 v43, v47, v36
	v_sub_f32_e32 v44, v55, v36
	v_sub_f32_e32 v36, v57, v36
	v_mul_f32_e32 v38, v37, v38
	v_mul_f32_e32 v39, v37, v39
	v_mul_f32_e32 v40, v37, v40
	v_mul_f32_e32 v41, v37, v41
	v_mul_f32_e32 v42, v37, v42
	v_mul_f32_e32 v43, v37, v43
	v_mul_f32_e32 v44, v37, v44
	v_mul_f32_e32 v36, v37, v36
	v_and_b32_e32 v45, 0xffff0000, v9
	v_lshlrev_b32_e32 v46, 16, v10
	v_and_b32_e32 v47, 0xffff0000, v10
	v_lshlrev_b32_e32 v55, 16, v11
	v_and_b32_e32 v57, 0xffff0000, v11
	s_waitcnt vmcnt(2)
	v_fma_f32 v16, v38, v20, v16
	v_fma_f32 v17, v39, v21, v17
	v_fma_f32 v18, v40, v22, v18
	v_fmac_f32_e32 v19, v41, v23
	s_waitcnt vmcnt(0)
; __device__ __forceinline__ unsigned cvt_pk_bf16(float lo, float hi) { unsigned r; asm volatile("v_cvt_pk_bf16_f32 %0, %1, %2" : "=v"(r) : "v"(lo), "v"(hi)); return r; }
; #define LAS __attribute__((address_space(3)))
; #define GAS __attribute__((address_space(1)))
; DI float bf_lo(unsigned w) { return __uint_as_float(w << 16); }
; DI float bf_hi(unsigned w) { return __uint_as_float(w & 0xffff0000u); }
; DI void phase_mix(const Ctx& C, bf16_t* Z, const float* lse_, int L, bool dry) {
;     ...
;         for (int cc = 0; cc < 4; ++cc) {
;             const int c = tid + cc * 512, tk = c >> 4, ch = c & 15, c0 = g * 128 + ch * 8;
;             const u32x4 rw = raw[cc];
;             const float mean = stat[tk * 2], rstd = stat[tk * 2 + 1];
;             const f32x4 g0 = *(const GAS f32x4*)(ln_g + c0), g1 = *(const GAS f32x4*)(ln_g + c0 + 4), b0 = *(const GAS f32x4*)(ln_b + c0), b1 = *(const GAS f32x4*)(ln_b + c0 + 4);
;             LAS bf16_t* vp = Vt2 + (ch * 8) * 136 + (tk ^ (ch << 3));
;             const unsigned p0 = cvt_pk_bf16((bf_lo(rw.x) - mean) * rstd * g0.x + b0.x, (bf_hi(rw.x) - mean) * rstd * g0.y + b0.y);
;             const unsigned p1 = cvt_pk_bf16((bf_lo(rw.y) - mean) * rstd * g0.z + b0.z, (bf_hi(rw.y) - mean) * rstd * g0.w + b0.w);
;             const unsigned p2 = cvt_pk_bf16((bf_lo(rw.z) - mean) * rstd * g1.x + b1.x, (bf_hi(rw.z) - mean) * rstd * g1.y + b1.y);
;             const unsigned p3 = cvt_pk_bf16((bf_lo(rw.w) - mean) * rstd * g1.z + b1.z, (bf_hi(rw.w) - mean) * rstd * g1.w + b1.w);
;             vp[0 * 136] = (bf16_t)(p0 & 0xffffu); vp[1 * 136] = (bf16_t)(p0 >> 16); vp[2 * 136] = (bf16_t)(p1 & 0xffffu); vp[3 * 136] = (bf16_t)(p1 >> 16);
;             vp[4 * 136] = (bf16_t)(p2 & 0xffffu); vp[5 * 136] = (bf16_t)(p2 >> 16); vp[6 * 136] = (bf16_t)(p3 & 0xffffu); vp[7 * 136] = (bf16_t)(p3 >> 16);
;         }
;         __syncthreads();
;         if (g < 3) {
; #pragma unroll
;             for (int cc = 0; cc < 4; ++cc) { const int c = tid + cc * 512, tk = c >> 4, ch = c & 15; raw[cc] = *(const GAS u32x4*)(Z + (size_t)(row0 + tk) * ZW + CVV + (g + 1) * 128 + ch * 8); }
;         }
	v_fma_f32 v20, v42, v28, v32
	v_fma_f32 v21, v43, v29, v33
	v_fma_f32 v22, v44, v30, v34
	v_fmac_f32_e32 v35, v36, v31
	v_cvt_pk_bf16_f32 v38, v16, v17
	v_cvt_pk_bf16_f32 v39, v18, v19
	v_cvt_pk_bf16_f32 v40, v20, v21
	v_cvt_pk_bf16_f32 v41, v22, v35
	v_mov_b32_e32 v16, v156
	v_mov_b32_e32 v17, v157
	v_mov_b32_e32 v18, v158
	v_mov_b32_e32 v19, v159
	v_mov_b32_e32 v20, v160
	v_mov_b32_e32 v21, v161
	v_mov_b32_e32 v22, v162
	v_mov_b32_e32 v23, v163
	v_mov_b32_e32 v28, v164
	v_mov_b32_e32 v29, v165
	v_mov_b32_e32 v30, v166
	v_mov_b32_e32 v31, v167
	v_mov_b32_e32 v32, v168
	v_mov_b32_e32 v33, v169
	v_mov_b32_e32 v34, v170
	v_mov_b32_e32 v35, v171
	ds_read_b64 v[36:37], v113 offset:34816
	v_lshlrev_b32_e32 v42, 16, v8
	v_and_b32_e32 v43, 0xffff0000, v8
	v_lshlrev_b32_e32 v44, 16, v9
	ds_write_b16 v99, v38
	ds_write_b16_d16_hi v99, v38 offset:272
	ds_write_b16 v99, v39 offset:544
	ds_write_b16_d16_hi v99, v39 offset:816
	ds_write_b16 v99, v40 offset:1088
	ds_write_b16_d16_hi v99, v40 offset:1360
	ds_write_b16 v99, v41 offset:1632
	ds_write_b16_d16_hi v99, v41 offset:1904
	s_waitcnt lgkmcnt(8)
	v_sub_f32_e32 v38, v42, v36
	v_sub_f32_e32 v39, v43, v36
	v_sub_f32_e32 v40, v44, v36
	v_sub_f32_e32 v41, v45, v36
	v_sub_f32_e32 v42, v46, v36
	v_sub_f32_e32 v43, v47, v36
	v_sub_f32_e32 v44, v55, v36
	v_sub_f32_e32 v36, v57, v36
	v_mul_f32_e32 v38, v37, v38
	v_mul_f32_e32 v39, v37, v39
	v_mul_f32_e32 v40, v37, v40
	v_mul_f32_e32 v41, v37, v41
	v_mul_f32_e32 v42, v37, v42
	v_mul_f32_e32 v43, v37, v43
	v_mul_f32_e32 v44, v37, v44
	v_mul_f32_e32 v36, v37, v36
	v_and_b32_e32 v45, 0xffff0000, v15
	s_waitcnt vmcnt(2)
	v_fma_f32 v16, v38, v20, v16
	v_fma_f32 v17, v39, v21, v17
	v_fma_f32 v18, v40, v22, v18
	v_fmac_f32_e32 v19, v41, v23
	s_waitcnt vmcnt(0)
	v_fma_f32 v20, v42, v28, v32
	v_fma_f32 v21, v43, v29, v33
	v_fma_f32 v22, v44, v30, v34
	v_fmac_f32_e32 v35, v36, v31
	v_cvt_pk_bf16_f32 v34, v16, v17
	v_cvt_pk_bf16_f32 v36, v18, v19
	v_cvt_pk_bf16_f32 v37, v20, v21
	v_cvt_pk_bf16_f32 v35, v22, v35
	v_mov_b32_e32 v16, v156
	v_mov_b32_e32 v17, v157
	v_mov_b32_e32 v18, v158
	v_mov_b32_e32 v19, v159
	v_mov_b32_e32 v20, v160
	v_mov_b32_e32 v21, v161
	v_mov_b32_e32 v22, v162
	v_mov_b32_e32 v23, v163
	v_mov_b32_e32 v28, v164
	v_mov_b32_e32 v29, v165
	v_mov_b32_e32 v30, v166
	v_mov_b32_e32 v31, v167
	s_nop 0
	v_mov_b32_e32 v24, v168
	v_mov_b32_e32 v25, v169
	v_mov_b32_e32 v26, v170
	v_mov_b32_e32 v27, v171
	ds_read_b64 v[32:33], v114 offset:34816
	v_lshlrev_b32_e32 v38, 16, v12
	v_and_b32_e32 v39, 0xffff0000, v12
	v_lshlrev_b32_e32 v40, 16, v13
	v_and_b32_e32 v41, 0xffff0000, v13
	ds_write_b16 v100, v34
	ds_write_b16_d16_hi v100, v34 offset:272
	ds_write_b16 v100, v36 offset:544
	ds_write_b16_d16_hi v100, v36 offset:816
	ds_write_b16 v100, v37 offset:1088
	ds_write_b16_d16_hi v100, v37 offset:1360
	ds_write_b16 v100, v35 offset:1632
	ds_write_b16_d16_hi v100, v35 offset:1904
	s_waitcnt lgkmcnt(8)
	v_sub_f32_e32 v34, v38, v32
	v_lshlrev_b32_e32 v42, 16, v14
	v_and_b32_e32 v43, 0xffff0000, v14
	v_lshlrev_b32_e32 v44, 16, v15
	v_sub_f32_e32 v35, v39, v32
	v_sub_f32_e32 v36, v40, v32
	v_sub_f32_e32 v37, v41, v32
	v_mul_f32_e32 v34, v33, v34
	v_sub_f32_e32 v38, v42, v32
	v_sub_f32_e32 v39, v43, v32
	v_sub_f32_e32 v40, v44, v32
	v_sub_f32_e32 v32, v45, v32
	v_mul_f32_e32 v35, v33, v35
	v_mul_f32_e32 v36, v33, v36
	v_mul_f32_e32 v37, v33, v37
	v_mul_f32_e32 v38, v33, v38
	v_mul_f32_e32 v39, v33, v39
	v_mul_f32_e32 v40, v33, v40
	v_mul_f32_e32 v32, v33, v32
	s_waitcnt vmcnt(2)
	v_fma_f32 v16, v34, v20, v16
	v_fma_f32 v17, v35, v21, v17
	v_fma_f32 v18, v36, v22, v18
	v_fmac_f32_e32 v19, v37, v23
	v_cvt_pk_bf16_f32 v16, v16, v17
	s_waitcnt vmcnt(0)
	v_fma_f32 v20, v38, v28, v24
	v_fma_f32 v21, v39, v29, v25
	v_fma_f32 v22, v40, v30, v26
	v_fmac_f32_e32 v27, v32, v31
	v_cvt_pk_bf16_f32 v17, v18, v19
	v_cvt_pk_bf16_f32 v18, v20, v21
	v_cvt_pk_bf16_f32 v19, v22, v27
	ds_write_b16 v101, v16
	ds_write_b16_d16_hi v101, v16 offset:272
	ds_write_b16 v101, v17 offset:544
	ds_write_b16_d16_hi v101, v17 offset:816
	ds_write_b16 v101, v18 offset:1088
	ds_write_b16_d16_hi v101, v18 offset:1360
	ds_write_b16 v101, v19 offset:1632
	ds_write_b16_d16_hi v101, v19 offset:1904
	s_waitcnt lgkmcnt(0)
	s_barrier
	s_cbranch_scc1 .LBB0_196
	s_lshl_b32 s1, s1, 1
	v_readlane_b32 s2, v253, 51
	v_readlane_b32 s3, v253, 52
	s_add_u32 s2, s2, s1
	s_addc_u32 s3, s3, 0
	v_lshl_add_u64 v[0:1], s[2:3], 0, v[58:59]
	v_mov_b32_e32 v57, v193
	v_lshl_add_u64 v[0:1], v[0:1], 0, v[56:57]
	v_add_co_u32_e32 v0, vcc, 0x2000, v0
	v_lshl_add_u64 v[2:3], s[2:3], 0, v[60:61]
	s_nop 0
	v_addc_co_u32_e32 v1, vcc, 0, v1, vcc
	v_lshl_add_u64 v[2:3], v[2:3], 0, v[56:57]
	v_add_co_u32_e32 v4, vcc, 0x2000, v2
	v_lshl_add_u64 v[8:9], s[2:3], 0, v[62:63]
	s_nop 0
	v_addc_co_u32_e32 v5, vcc, 0, v3, vcc
	v_lshl_add_u64 v[8:9], v[8:9], 0, v[56:57]
	v_add_co_u32_e32 v8, vcc, 0x2000, v8
	v_lshl_add_u64 v[10:11], s[2:3], 0, v[64:65]
	s_nop 0
	v_addc_co_u32_e32 v9, vcc, 0, v9, vcc
	v_lshl_add_u64 v[10:11], v[10:11], 0, v[56:57]
	v_add_co_u32_e32 v12, vcc, 0x2000, v10
	global_load_dwordx4 v[0:3], v[0:1], off offset:768
	s_nop 0
	global_load_dwordx4 v[4:7], v[4:5], off offset:768
	v_addc_co_u32_e32 v13, vcc, 0, v11, vcc
	global_load_dwordx4 v[8:11], v[8:9], off offset:768
	s_nop 0
	global_load_dwordx4 v[12:15], v[12:13], off offset:768
